# in-proj epilogue: V^T tiles staged through a 1 KiB per-wave LDS block and written with one 16-byte store per lane instead of eight 2-byte scattered stores
# baseline (speedup 1.0000x reference)
.LBB0_540:
	s_lshl_b32 s4, s27, 5
	s_waitcnt lgkmcnt(0)
	v_lshlrev_b32_e32 v218, 3, v246
	v_add_u32_e32 v220, s4, v218
	v_add_u32_e32 v250, s4, v220
	s_lshl_b32 s4, s30, 6
	s_ashr_i32 s5, s4, 31
	s_xor_b64 s[14:15], s[14:15], -1
	s_xor_b64 s[72:73], s[42:43], -1
	s_xor_b64 s[42:43], s[16:17], -1
	s_xor_b64 s[0:1], s[10:11], -1
	s_lshl_b64 s[4:5], s[4:5], 1
	v_ashrrev_i32_e32 v0, 1, v246
	s_add_u32 s4, s54, s4
	v_lshl_add_u32 v227, s27, 1, v0
	v_lshlrev_b32_e32 v0, 5, v246
	v_ashrrev_i32_e32 v221, 31, v220
	s_addc_u32 s5, s55, s5
	v_mov_b64_e32 v[248:249], 0x5ff
	v_ashrrev_i32_e32 v252, 11, v226
	v_and_b32_e32 v225, 0x7ff, v226
	v_and_b32_e32 v198, 3, v245
	v_and_b32_e32 v234, 32, v0
	v_lshl_add_u64 v[222:223], v[220:221], 1, s[4:5]
	v_cmp_lt_i32_e64 s[10:11], 2, v246
	v_and_b32_e32 v251, 31, v245
	s_mov_b64 s[4:5], -1
	s_and_b64 vcc, exec, s[14:15]
	s_cbranch_vccz .LBB0_555
	v_cvt_pk_bf16_f32 v194, v186, v187
	v_cvt_pk_bf16_f32 v195, v188, v189
	v_cvt_pk_bf16_f32 v196, v190, v191
	v_cvt_pk_bf16_f32 v197, v192, v193
	s_and_b64 vcc, exec, s[72:73]
	s_cbranch_vccz .LBB0_551
	v_mov_b32_e32 v0, s30
	v_mad_i32_i24 v202, s48, v252, v0
	v_ashrrev_i32_e32 v203, 31, v202
	v_lshlrev_b64 v[202:203], 18, v[202:203]
	s_and_b64 vcc, exec, s[42:43]
	v_lshlrev_b32_e32 v228, 7, v225
	v_lshl_add_u64 v[230:231], s[54:55], 0, v[202:203]
	s_cbranch_vccz .LBB0_548
	v_and_b32_e32 v0, 0x3e000, v228
	v_lshl_add_u64 v[232:233], v[230:231], 0, v[0:1]
	s_and_b64 vcc, exec, s[0:1]
	s_cbranch_vccz .LBB0_545
	v_lshlrev_b32_e32 v0, 3, v245
	v_and_b32_e32 v0, 0x1a0, v0
	v_add_lshl_u32 v202, v250, v0, 3
	v_ashrrev_i32_e32 v203, 31, v202
	v_lshl_add_u64 v[202:203], v[202:203], 1, v[232:233]
	v_and_b32_e32 v0, 8, v245
	v_lshl_add_u64 v[202:203], v[202:203], 0, v[0:1]
	v_lshlrev_b32_e32 v0, 1, v198
	v_lshl_add_u64 v[202:203], v[202:203], 0, v[0:1]
	s_lshl_b32 s31, s66, 2
	s_add_i32 s31, s31, s67
	s_lshl_b32 s31, s31, 10
	s_add_i32 s31, s31, 0x20000
	v_and_b32_e32 v0, 15, v240
	v_lshrrev_b32_e32 v205, 4, v240
	v_bfe_u32 v229, v0, 2, 1
	v_lshl_add_u32 v205, v229, 2, v205
	v_lshlrev_b32_e32 v205, 6, v205
	v_bfe_u32 v229, v0, 3, 1
	v_lshl_add_u32 v205, v229, 2, v205
	v_and_b32_e32 v0, 3, v0
	v_add_lshl_u32 v205, v205, v0, 1
	v_lshlrev_b32_e32 v0, 4, v240
	v_sub_u32_e32 v229, v0, v205
	v_add_u32_e32 v205, s31, v205
	v_add_u32_e32 v0, s31, v0
	ds_write_b16 v205, v194
	ds_write_b16_d16_hi v205, v194 offset:16
	ds_write_b16 v205, v195 offset:32
	ds_write_b16_d16_hi v205, v195 offset:48
	ds_write_b16 v205, v196 offset:64
	ds_write_b16_d16_hi v205, v196 offset:80
	ds_write_b16 v205, v197 offset:96
	ds_write_b16_d16_hi v205, v197 offset:112
	v_ashrrev_i32_e32 v205, 31, v229
	v_add_co_u32_e32 v202, vcc, v202, v229
	s_nop 1
	v_addc_co_u32_e32 v203, vcc, v203, v205, vcc
	s_waitcnt lgkmcnt(0)
	ds_read_b128 v[194:197], v0
	s_waitcnt lgkmcnt(0)
	global_store_dwordx4 v[202:203], v[194:197], off
	s_mov_b64 s[4:5], 0

.LBB0_580:
	s_waitcnt lgkmcnt(0)
	v_add_u32_e32 v191, 16, v247
	v_cndmask_b32_e64 v0, 0, 1, s[14:15]
	v_add_u32_e32 v197, s49, v191
	v_cmp_ne_u32_e64 s[16:17], 1, v0
	v_cndmask_b32_e64 v0, 0, 1, s[72:73]
	v_ashrrev_i32_e32 v225, 11, v197
	v_and_b32_e32 v228, 0x7ff, v197
	v_xor_b32_e32 v196, 16, v251
	s_mov_b64 s[4:5], -1
	s_andn2_b64 vcc, exec, s[14:15]
	v_cmp_ne_u32_e64 s[14:15], 1, v0
	s_cbranch_vccnz .LBB0_595
	v_cvt_pk_bf16_f32 v186, v178, v179
	v_cvt_pk_bf16_f32 v187, v180, v181
	v_cvt_pk_bf16_f32 v188, v182, v183
	v_cvt_pk_bf16_f32 v189, v184, v185
	s_and_b64 vcc, exec, s[14:15]
	s_cbranch_vccnz .LBB0_591
	v_mov_b32_e32 v0, s30
	v_mad_i32_i24 v192, s48, v225, v0
	v_ashrrev_i32_e32 v193, 31, v192
	v_lshlrev_b64 v[192:193], 18, v[192:193]
	s_andn2_b64 vcc, exec, s[42:43]
	v_lshlrev_b32_e32 v190, 7, v228
	v_lshl_add_u64 v[192:193], s[54:55], 0, v[192:193]
	s_cbranch_vccnz .LBB0_588
	v_and_b32_e32 v0, 0x3e000, v190
	v_lshl_add_u64 v[194:195], v[192:193], 0, v[0:1]
	s_andn2_b64 vcc, exec, s[0:1]
	s_cbranch_vccnz .LBB0_585
	v_lshlrev_b32_e32 v202, 3, v245
	v_lshlrev_b32_e32 v0, 3, v191
	v_and_b32_e32 v202, 32, v202
	v_and_b32_e32 v0, 0x180, v0
	v_add_u32_e32 v202, v250, v202
	v_add_lshl_u32 v202, v202, v0, 3
	v_ashrrev_i32_e32 v203, 31, v202
	v_lshl_add_u64 v[202:203], v[202:203], 1, v[194:195]
	v_and_b32_e32 v0, 8, v245
	v_lshl_add_u64 v[202:203], v[202:203], 0, v[0:1]
	v_lshlrev_b32_e32 v0, 1, v198
	v_lshl_add_u64 v[202:203], v[202:203], 0, v[0:1]
	s_mov_b64 s[4:5], 0
	s_lshl_b32 s31, s66, 2
	s_add_i32 s31, s31, s67
	s_lshl_b32 s31, s31, 10
	s_add_i32 s31, s31, 0x20000
	v_and_b32_e32 v0, 15, v240
	v_lshrrev_b32_e32 v205, 4, v240
	v_bfe_u32 v229, v0, 2, 1
	v_lshl_add_u32 v205, v229, 2, v205
	v_lshlrev_b32_e32 v205, 6, v205
	v_bfe_u32 v229, v0, 3, 1
	v_lshl_add_u32 v205, v229, 2, v205
	v_and_b32_e32 v0, 3, v0
	v_add_lshl_u32 v205, v205, v0, 1
	v_lshlrev_b32_e32 v0, 4, v240
	v_sub_u32_e32 v229, v0, v205
	v_add_u32_e32 v205, s31, v205
	v_add_u32_e32 v0, s31, v0
	ds_write_b16 v205, v186
	ds_write_b16_d16_hi v205, v186 offset:16
	ds_write_b16 v205, v187 offset:32
	ds_write_b16_d16_hi v205, v187 offset:48
	ds_write_b16 v205, v188 offset:64
	ds_write_b16_d16_hi v205, v188 offset:80
	ds_write_b16 v205, v189 offset:96
	ds_write_b16_d16_hi v205, v189 offset:112
	v_ashrrev_i32_e32 v205, 31, v229
	v_add_co_u32_e32 v202, vcc, v202, v229
	s_nop 1
	v_addc_co_u32_e32 v203, vcc, v203, v205, vcc
	s_waitcnt lgkmcnt(0)
	ds_read_b128 v[186:189], v0
	s_waitcnt lgkmcnt(0)
	global_store_dwordx4 v[202:203], v[186:189], off

.LBB0_620:
	s_waitcnt lgkmcnt(0)
	v_add_u32_e32 v183, 32, v247
	v_add_u32_e32 v188, s49, v183
	v_ashrrev_i32_e32 v189, 11, v188
	v_and_b32_e32 v190, 0x7ff, v188
	s_and_b64 vcc, exec, s[16:17]
	s_mov_b64 s[4:5], -1
	s_cbranch_vccnz .LBB0_635
	v_cvt_pk_bf16_f32 v178, v170, v171
	v_cvt_pk_bf16_f32 v179, v172, v173
	v_cvt_pk_bf16_f32 v180, v174, v175
	v_cvt_pk_bf16_f32 v181, v176, v177
	s_and_b64 vcc, exec, s[14:15]
	s_cbranch_vccnz .LBB0_631
	v_mov_b32_e32 v0, s30
	v_mad_i32_i24 v184, s48, v189, v0
	v_ashrrev_i32_e32 v185, 31, v184
	v_lshlrev_b64 v[184:185], 18, v[184:185]
	s_andn2_b64 vcc, exec, s[42:43]
	v_lshlrev_b32_e32 v182, 7, v190
	v_lshl_add_u64 v[184:185], s[54:55], 0, v[184:185]
	s_cbranch_vccnz .LBB0_628
	v_and_b32_e32 v0, 0x3e000, v182
	v_lshl_add_u64 v[186:187], v[184:185], 0, v[0:1]
	s_andn2_b64 vcc, exec, s[0:1]
	s_cbranch_vccnz .LBB0_625
	v_lshlrev_b32_e32 v191, 3, v245
	v_lshlrev_b32_e32 v0, 3, v183
	v_and_b32_e32 v191, 32, v191
	v_and_b32_e32 v0, 0x180, v0
	v_add_u32_e32 v191, v250, v191
	v_add_lshl_u32 v192, v191, v0, 3
	v_ashrrev_i32_e32 v193, 31, v192
	v_lshl_add_u64 v[192:193], v[192:193], 1, v[186:187]
	v_and_b32_e32 v0, 8, v245
	v_lshl_add_u64 v[192:193], v[192:193], 0, v[0:1]
	v_lshlrev_b32_e32 v0, 1, v198
	v_lshl_add_u64 v[192:193], v[192:193], 0, v[0:1]
	s_mov_b64 s[4:5], 0
	s_lshl_b32 s31, s66, 2
	s_add_i32 s31, s31, s67
	s_lshl_b32 s31, s31, 10
	s_add_i32 s31, s31, 0x20000
	v_and_b32_e32 v0, 15, v240
	v_lshrrev_b32_e32 v205, 4, v240
	v_bfe_u32 v229, v0, 2, 1
	v_lshl_add_u32 v205, v229, 2, v205
	v_lshlrev_b32_e32 v205, 6, v205
	v_bfe_u32 v229, v0, 3, 1
	v_lshl_add_u32 v205, v229, 2, v205
	v_and_b32_e32 v0, 3, v0
	v_add_lshl_u32 v205, v205, v0, 1
	v_lshlrev_b32_e32 v0, 4, v240
	v_sub_u32_e32 v229, v0, v205
	v_add_u32_e32 v205, s31, v205
	v_add_u32_e32 v0, s31, v0
	ds_write_b16 v205, v178
	ds_write_b16_d16_hi v205, v178 offset:16
	ds_write_b16 v205, v179 offset:32
	ds_write_b16_d16_hi v205, v179 offset:48
	ds_write_b16 v205, v180 offset:64
	ds_write_b16_d16_hi v205, v180 offset:80
	ds_write_b16 v205, v181 offset:96
	ds_write_b16_d16_hi v205, v181 offset:112
	v_ashrrev_i32_e32 v205, 31, v229
	v_add_co_u32_e32 v192, vcc, v192, v229
	s_nop 1
	v_addc_co_u32_e32 v193, vcc, v193, v205, vcc
	s_waitcnt lgkmcnt(0)
	ds_read_b128 v[178:181], v0
	s_waitcnt lgkmcnt(0)
	global_store_dwordx4 v[192:193], v[178:181], off

.LBB0_660:
	s_waitcnt lgkmcnt(0)
	v_add_u32_e32 v175, 48, v247
	v_add_u32_e32 v180, s49, v175
	v_ashrrev_i32_e32 v181, 11, v180
	v_and_b32_e32 v182, 0x7ff, v180
	s_and_b64 vcc, exec, s[16:17]
	s_mov_b64 s[4:5], -1
	s_cbranch_vccnz .LBB0_676
	v_cvt_pk_bf16_f32 v170, v146, v147
	v_cvt_pk_bf16_f32 v171, v148, v149
	v_cvt_pk_bf16_f32 v172, v166, v167
	v_cvt_pk_bf16_f32 v173, v168, v169
	s_and_b64 vcc, exec, s[14:15]
	s_cbranch_vccnz .LBB0_671
	v_mov_b32_e32 v0, s30
	v_mad_i32_i24 v176, s48, v181, v0
	v_ashrrev_i32_e32 v177, 31, v176
	v_lshlrev_b64 v[176:177], 18, v[176:177]
	s_andn2_b64 vcc, exec, s[42:43]
	v_lshlrev_b32_e32 v174, 7, v182
	v_lshl_add_u64 v[176:177], s[54:55], 0, v[176:177]
	s_cbranch_vccnz .LBB0_668
	v_and_b32_e32 v0, 0x3e000, v174
	v_lshl_add_u64 v[178:179], v[176:177], 0, v[0:1]
	s_andn2_b64 vcc, exec, s[0:1]
	s_cbranch_vccnz .LBB0_665
	v_lshlrev_b32_e32 v183, 3, v245
	v_lshlrev_b32_e32 v0, 3, v175
	v_and_b32_e32 v183, 32, v183
	v_and_b32_e32 v0, 0x180, v0
	v_add_u32_e32 v183, v250, v183
	v_add_lshl_u32 v184, v183, v0, 3
	v_ashrrev_i32_e32 v185, 31, v184
	v_lshl_add_u64 v[184:185], v[184:185], 1, v[178:179]
	v_and_b32_e32 v0, 8, v245
	v_lshl_add_u64 v[184:185], v[184:185], 0, v[0:1]
	v_lshlrev_b32_e32 v0, 1, v198
	v_lshl_add_u64 v[184:185], v[184:185], 0, v[0:1]
	s_mov_b64 s[4:5], 0
	s_lshl_b32 s31, s66, 2
	s_add_i32 s31, s31, s67
	s_lshl_b32 s31, s31, 10
	s_add_i32 s31, s31, 0x20000
	v_and_b32_e32 v0, 15, v240
	v_lshrrev_b32_e32 v205, 4, v240
	v_bfe_u32 v229, v0, 2, 1
	v_lshl_add_u32 v205, v229, 2, v205
	v_lshlrev_b32_e32 v205, 6, v205
	v_bfe_u32 v229, v0, 3, 1
	v_lshl_add_u32 v205, v229, 2, v205
	v_and_b32_e32 v0, 3, v0
	v_add_lshl_u32 v205, v205, v0, 1
	v_lshlrev_b32_e32 v0, 4, v240
	v_sub_u32_e32 v229, v0, v205
	v_add_u32_e32 v205, s31, v205
	v_add_u32_e32 v0, s31, v0
	ds_write_b16 v205, v170
	ds_write_b16_d16_hi v205, v170 offset:16
	ds_write_b16 v205, v171 offset:32
	ds_write_b16_d16_hi v205, v171 offset:48
	ds_write_b16 v205, v172 offset:64
	ds_write_b16_d16_hi v205, v172 offset:80
	ds_write_b16 v205, v173 offset:96
	ds_write_b16_d16_hi v205, v173 offset:112
	v_ashrrev_i32_e32 v205, 31, v229
	v_add_co_u32_e32 v184, vcc, v184, v229
	s_nop 1
	v_addc_co_u32_e32 v185, vcc, v185, v205, vcc
	s_waitcnt lgkmcnt(0)
	ds_read_b128 v[170:173], v0
	s_waitcnt lgkmcnt(0)
	global_store_dwordx4 v[184:185], v[170:173], off

.LBB0_702:
	s_waitcnt vmcnt(0)
	v_ashrrev_i32_e32 v156, 11, v166
	v_and_b32_e32 v157, 0x7ff, v166
	s_and_b64 vcc, exec, s[16:17]
	s_mov_b64 s[4:5], -1
	s_cbranch_vccnz .LBB0_717
	s_waitcnt lgkmcnt(5)
	v_cvt_pk_bf16_f32 v146, v122, v123
	s_waitcnt lgkmcnt(4)
	v_cvt_pk_bf16_f32 v147, v124, v125
	v_cvt_pk_bf16_f32 v148, v126, v127
	v_cvt_pk_bf16_f32 v149, v128, v129
	s_and_b64 vcc, exec, s[14:15]
	s_cbranch_vccnz .LBB0_713
	s_waitcnt lgkmcnt(0)
	v_mov_b32_e32 v0, s30
	v_mad_i32_i24 v150, s48, v156, v0
	v_ashrrev_i32_e32 v151, 31, v150
	v_lshlrev_b64 v[152:153], 18, v[150:151]
	s_andn2_b64 vcc, exec, s[42:43]
	v_lshlrev_b32_e32 v150, 7, v157
	v_lshl_add_u64 v[152:153], s[54:55], 0, v[152:153]
	s_cbranch_vccnz .LBB0_710
	v_and_b32_e32 v0, 0x3e000, v150
	v_lshl_add_u64 v[154:155], v[152:153], 0, v[0:1]
	s_andn2_b64 vcc, exec, s[0:1]
	s_cbranch_vccnz .LBB0_707
	v_lshlrev_b32_e32 v0, 3, v245
	v_and_b32_e32 v0, 0x1a0, v0
	v_add_lshl_u32 v158, v250, v0, 3
	v_ashrrev_i32_e32 v159, 31, v158
	v_lshl_add_u64 v[158:159], v[158:159], 1, v[154:155]
	v_and_b32_e32 v0, 8, v245
	v_lshl_add_u64 v[158:159], v[158:159], 0, v[0:1]
	v_lshlrev_b32_e32 v0, 1, v198
	v_lshl_add_u64 v[158:159], v[158:159], 0, v[0:1]
	s_mov_b64 s[4:5], 0
	s_lshl_b32 s31, s66, 2
	s_add_i32 s31, s31, s67
	s_lshl_b32 s31, s31, 10
	s_add_i32 s31, s31, 0x20000
	v_and_b32_e32 v0, 15, v240
	v_lshrrev_b32_e32 v205, 4, v240
	v_bfe_u32 v229, v0, 2, 1
	v_lshl_add_u32 v205, v229, 2, v205
	v_lshlrev_b32_e32 v205, 6, v205
	v_bfe_u32 v229, v0, 3, 1
	v_lshl_add_u32 v205, v229, 2, v205
	v_and_b32_e32 v0, 3, v0
	v_add_lshl_u32 v205, v205, v0, 1
	v_lshlrev_b32_e32 v0, 4, v240
	v_sub_u32_e32 v229, v0, v205
	v_add_u32_e32 v205, s31, v205
	v_add_u32_e32 v0, s31, v0
	ds_write_b16 v205, v146
	ds_write_b16_d16_hi v205, v146 offset:16
	ds_write_b16 v205, v147 offset:32
	ds_write_b16_d16_hi v205, v147 offset:48
	ds_write_b16 v205, v148 offset:64
	ds_write_b16_d16_hi v205, v148 offset:80
	ds_write_b16 v205, v149 offset:96
	ds_write_b16_d16_hi v205, v149 offset:112
	v_ashrrev_i32_e32 v205, 31, v229
	v_add_co_u32_e32 v158, vcc, v158, v229
	s_nop 1
	v_addc_co_u32_e32 v159, vcc, v159, v205, vcc
	s_waitcnt lgkmcnt(0)
	ds_read_b128 v[146:149], v0
	s_waitcnt lgkmcnt(0)
	global_store_dwordx4 v[158:159], v[146:149], off

.LBB0_742:
	s_waitcnt lgkmcnt(2)
	v_add_u32_e32 v127, 0x90, v247
	v_add_u32_e32 v132, s49, v127
	v_ashrrev_i32_e32 v133, 11, v132
	v_and_b32_e32 v134, 0x7ff, v132
	s_and_b64 vcc, exec, s[16:17]
	s_mov_b64 s[4:5], -1
	s_cbranch_vccnz .LBB0_757
	v_cvt_pk_bf16_f32 v122, v98, v99
	v_cvt_pk_bf16_f32 v123, v100, v101
	v_cvt_pk_bf16_f32 v124, v102, v103
	v_cvt_pk_bf16_f32 v125, v104, v105
	s_and_b64 vcc, exec, s[14:15]
	s_cbranch_vccnz .LBB0_753
	s_waitcnt lgkmcnt(0)
	v_mov_b32_e32 v0, s30
	v_mad_i32_i24 v128, s48, v133, v0
	v_ashrrev_i32_e32 v129, 31, v128
	v_lshlrev_b64 v[128:129], 18, v[128:129]
	s_andn2_b64 vcc, exec, s[42:43]
	v_lshlrev_b32_e32 v126, 7, v134
	v_lshl_add_u64 v[128:129], s[54:55], 0, v[128:129]
	s_cbranch_vccnz .LBB0_750
	v_and_b32_e32 v0, 0x3e000, v126
	v_lshl_add_u64 v[130:131], v[128:129], 0, v[0:1]
	s_andn2_b64 vcc, exec, s[0:1]
	s_cbranch_vccnz .LBB0_747
	v_lshlrev_b32_e32 v135, 3, v245
	v_lshlrev_b32_e32 v0, 3, v127
	v_and_b32_e32 v135, 32, v135
	v_and_b32_e32 v0, 0x180, v0
	v_add_u32_e32 v135, v250, v135
	v_add_lshl_u32 v136, v135, v0, 3
	v_ashrrev_i32_e32 v137, 31, v136
	v_lshl_add_u64 v[136:137], v[136:137], 1, v[130:131]
	v_and_b32_e32 v0, 8, v245
	v_lshl_add_u64 v[136:137], v[136:137], 0, v[0:1]
	v_lshlrev_b32_e32 v0, 1, v198
	v_lshl_add_u64 v[136:137], v[136:137], 0, v[0:1]
	s_mov_b64 s[4:5], 0
	s_lshl_b32 s31, s66, 2
	s_add_i32 s31, s31, s67
	s_lshl_b32 s31, s31, 10
	s_add_i32 s31, s31, 0x20000
	v_and_b32_e32 v0, 15, v240
	v_lshrrev_b32_e32 v205, 4, v240
	v_bfe_u32 v229, v0, 2, 1
	v_lshl_add_u32 v205, v229, 2, v205
	v_lshlrev_b32_e32 v205, 6, v205
	v_bfe_u32 v229, v0, 3, 1
	v_lshl_add_u32 v205, v229, 2, v205
	v_and_b32_e32 v0, 3, v0
	v_add_lshl_u32 v205, v205, v0, 1
	v_lshlrev_b32_e32 v0, 4, v240
	v_sub_u32_e32 v229, v0, v205
	v_add_u32_e32 v205, s31, v205
	v_add_u32_e32 v0, s31, v0
	ds_write_b16 v205, v122
	ds_write_b16_d16_hi v205, v122 offset:16
	ds_write_b16 v205, v123 offset:32
	ds_write_b16_d16_hi v205, v123 offset:48
	ds_write_b16 v205, v124 offset:64
	ds_write_b16_d16_hi v205, v124 offset:80
	ds_write_b16 v205, v125 offset:96
	ds_write_b16_d16_hi v205, v125 offset:112
	v_ashrrev_i32_e32 v205, 31, v229
	v_add_co_u32_e32 v136, vcc, v136, v229
	s_nop 1
	v_addc_co_u32_e32 v137, vcc, v137, v205, vcc
	s_waitcnt lgkmcnt(0)
	ds_read_b128 v[122:125], v0
	s_waitcnt lgkmcnt(0)
	global_store_dwordx4 v[136:137], v[122:125], off

.LBB0_782:
	s_waitcnt lgkmcnt(2)
	v_add_u32_e32 v103, 0xa0, v247
	v_add_u32_e32 v108, s49, v103
	v_ashrrev_i32_e32 v109, 11, v108
	v_and_b32_e32 v110, 0x7ff, v108
	s_and_b64 vcc, exec, s[16:17]
	s_mov_b64 s[4:5], -1
	s_cbranch_vccnz .LBB0_797
	v_cvt_pk_bf16_f32 v98, v74, v75
	v_cvt_pk_bf16_f32 v99, v76, v77
	v_cvt_pk_bf16_f32 v100, v78, v79
	v_cvt_pk_bf16_f32 v101, v80, v81
	s_and_b64 vcc, exec, s[14:15]
	s_cbranch_vccnz .LBB0_793
	s_waitcnt lgkmcnt(0)
	v_mov_b32_e32 v0, s30
	v_mad_i32_i24 v104, s48, v109, v0
	v_ashrrev_i32_e32 v105, 31, v104
	v_lshlrev_b64 v[104:105], 18, v[104:105]
	s_andn2_b64 vcc, exec, s[42:43]
	v_lshlrev_b32_e32 v102, 7, v110
	v_lshl_add_u64 v[104:105], s[54:55], 0, v[104:105]
	s_cbranch_vccnz .LBB0_790
	v_and_b32_e32 v0, 0x3e000, v102
	v_lshl_add_u64 v[106:107], v[104:105], 0, v[0:1]
	s_andn2_b64 vcc, exec, s[0:1]
	s_cbranch_vccnz .LBB0_787
	v_lshlrev_b32_e32 v111, 3, v245
	v_lshlrev_b32_e32 v0, 3, v103
	v_and_b32_e32 v111, 32, v111
	v_and_b32_e32 v0, 0x180, v0
	v_add_u32_e32 v111, v250, v111
	v_add_lshl_u32 v112, v111, v0, 3
	v_ashrrev_i32_e32 v113, 31, v112
	v_lshl_add_u64 v[112:113], v[112:113], 1, v[106:107]
	v_and_b32_e32 v0, 8, v245
	v_lshl_add_u64 v[112:113], v[112:113], 0, v[0:1]
	v_lshlrev_b32_e32 v0, 1, v198
	v_lshl_add_u64 v[112:113], v[112:113], 0, v[0:1]
	s_mov_b64 s[4:5], 0
	s_lshl_b32 s31, s66, 2
	s_add_i32 s31, s31, s67
	s_lshl_b32 s31, s31, 10
	s_add_i32 s31, s31, 0x20000
	v_and_b32_e32 v0, 15, v240
	v_lshrrev_b32_e32 v205, 4, v240
	v_bfe_u32 v229, v0, 2, 1
	v_lshl_add_u32 v205, v229, 2, v205
	v_lshlrev_b32_e32 v205, 6, v205
	v_bfe_u32 v229, v0, 3, 1
	v_lshl_add_u32 v205, v229, 2, v205
	v_and_b32_e32 v0, 3, v0
	v_add_lshl_u32 v205, v205, v0, 1
	v_lshlrev_b32_e32 v0, 4, v240
	v_sub_u32_e32 v229, v0, v205
	v_add_u32_e32 v205, s31, v205
	v_add_u32_e32 v0, s31, v0
	ds_write_b16 v205, v98
	ds_write_b16_d16_hi v205, v98 offset:16
	ds_write_b16 v205, v99 offset:32
	ds_write_b16_d16_hi v205, v99 offset:48
	ds_write_b16 v205, v100 offset:64
	ds_write_b16_d16_hi v205, v100 offset:80
	ds_write_b16 v205, v101 offset:96
	ds_write_b16_d16_hi v205, v101 offset:112
	v_ashrrev_i32_e32 v205, 31, v229
	v_add_co_u32_e32 v112, vcc, v112, v229
	s_nop 1
	v_addc_co_u32_e32 v113, vcc, v113, v205, vcc
	s_waitcnt lgkmcnt(0)
	ds_read_b128 v[98:101], v0
	s_waitcnt lgkmcnt(0)
	global_store_dwordx4 v[112:113], v[98:101], off

.LBB0_822:
	s_waitcnt lgkmcnt(2)
	v_add_u32_e32 v79, 0xb0, v247
	v_add_u32_e32 v84, s49, v79
	v_ashrrev_i32_e32 v85, 11, v84
	v_and_b32_e32 v86, 0x7ff, v84
	s_and_b64 vcc, exec, s[16:17]
	s_mov_b64 s[4:5], -1
	s_cbranch_vccnz .LBB0_836
	v_cvt_pk_bf16_f32 v74, v66, v67
	v_cvt_pk_bf16_f32 v75, v68, v69
	v_cvt_pk_bf16_f32 v76, v70, v71
	v_cvt_pk_bf16_f32 v77, v72, v73
	s_and_b64 vcc, exec, s[14:15]
	s_cbranch_vccnz .LBB0_833
	s_waitcnt lgkmcnt(0)
	v_mov_b32_e32 v0, s30
	v_mad_i32_i24 v80, s48, v85, v0
	v_ashrrev_i32_e32 v81, 31, v80
	v_lshlrev_b64 v[80:81], 18, v[80:81]
	s_andn2_b64 vcc, exec, s[42:43]
	v_lshlrev_b32_e32 v78, 7, v86
	v_lshl_add_u64 v[80:81], s[54:55], 0, v[80:81]
	s_cbranch_vccnz .LBB0_830
	v_and_b32_e32 v0, 0x3e000, v78
	v_lshl_add_u64 v[82:83], v[80:81], 0, v[0:1]
	s_andn2_b64 vcc, exec, s[0:1]
	s_mov_b64 s[0:1], -1
	s_cbranch_vccnz .LBB0_827
	v_lshlrev_b32_e32 v87, 3, v245
	v_lshlrev_b32_e32 v0, 3, v79
	v_and_b32_e32 v87, 32, v87
	v_and_b32_e32 v0, 0x180, v0
	v_add_u32_e32 v87, v250, v87
	v_add_lshl_u32 v88, v87, v0, 3
	v_ashrrev_i32_e32 v89, 31, v88
	v_lshl_add_u64 v[88:89], v[88:89], 1, v[82:83]
	v_and_b32_e32 v0, 8, v245
	v_lshl_add_u64 v[88:89], v[88:89], 0, v[0:1]
	v_lshlrev_b32_e32 v0, 1, v198
	v_lshl_add_u64 v[88:89], v[88:89], 0, v[0:1]
	s_mov_b64 s[0:1], 0
	s_lshl_b32 s31, s66, 2
	s_add_i32 s31, s31, s67
	s_lshl_b32 s31, s31, 10
	s_add_i32 s31, s31, 0x20000
	v_and_b32_e32 v0, 15, v240
	v_lshrrev_b32_e32 v205, 4, v240
	v_bfe_u32 v229, v0, 2, 1
	v_lshl_add_u32 v205, v229, 2, v205
	v_lshlrev_b32_e32 v205, 6, v205
	v_bfe_u32 v229, v0, 3, 1
	v_lshl_add_u32 v205, v229, 2, v205
	v_and_b32_e32 v0, 3, v0
	v_add_lshl_u32 v205, v205, v0, 1
	v_lshlrev_b32_e32 v0, 4, v240
	v_sub_u32_e32 v229, v0, v205
	v_add_u32_e32 v205, s31, v205
	v_add_u32_e32 v0, s31, v0
	ds_write_b16 v205, v74
	ds_write_b16_d16_hi v205, v74 offset:16
	ds_write_b16 v205, v75 offset:32
	ds_write_b16_d16_hi v205, v75 offset:48
	ds_write_b16 v205, v76 offset:64
	ds_write_b16_d16_hi v205, v76 offset:80
	ds_write_b16 v205, v77 offset:96
	ds_write_b16_d16_hi v205, v77 offset:112
	v_ashrrev_i32_e32 v205, 31, v229
	v_add_co_u32_e32 v88, vcc, v88, v229
	s_nop 1
	v_addc_co_u32_e32 v89, vcc, v89, v205, vcc
	s_waitcnt lgkmcnt(0)
	ds_read_b128 v[74:77], v0
	s_waitcnt lgkmcnt(0)
	global_store_dwordx4 v[88:89], v[74:77], off

.LBB0_917:
	s_lshl_b32 s4, s27, 5
	s_waitcnt lgkmcnt(0)
	v_lshlrev_b32_e32 v134, 3, v246
	v_add_u32_e32 v136, s4, v134
	v_add_u32_e32 v152, s4, v136
	s_lshl_b32 s4, s29, 6
	s_ashr_i32 s5, s4, 31
	s_xor_b64 s[14:15], s[14:15], -1
	s_xor_b64 s[42:43], s[42:43], -1
	s_xor_b64 s[22:23], s[16:17], -1
	s_xor_b64 s[0:1], s[10:11], -1
	s_lshl_b64 s[4:5], s[4:5], 1
	v_ashrrev_i32_e32 v0, 1, v246
	s_add_u32 s4, s54, s4
	v_lshl_add_u32 v143, s27, 1, v0
	v_lshlrev_b32_e32 v0, 5, v246
	v_ashrrev_i32_e32 v137, 31, v136
	s_addc_u32 s5, s55, s5
	v_ashrrev_i32_e32 v154, 11, v142
	v_and_b32_e32 v155, 0x7ff, v142
	v_and_b32_e32 v151, 3, v245
	v_and_b32_e32 v150, 32, v0
	v_lshl_add_u64 v[138:139], v[136:137], 1, s[4:5]
	v_cmp_lt_i32_e64 s[10:11], 2, v246
	v_and_b32_e32 v153, 31, v245
	s_mov_b64 s[4:5], -1
	s_and_b64 vcc, exec, s[14:15]
	s_cbranch_vccz .LBB0_932
	v_cvt_pk_bf16_f32 v130, v58, v59
	v_cvt_pk_bf16_f32 v131, v60, v61
	v_cvt_pk_bf16_f32 v132, v62, v63
	v_cvt_pk_bf16_f32 v133, v64, v65
	s_and_b64 vcc, exec, s[42:43]
	s_cbranch_vccz .LBB0_928
	v_mov_b32_e32 v0, s29
	v_mad_i32_i24 v144, s30, v154, v0
	v_ashrrev_i32_e32 v145, 31, v144
	v_lshlrev_b64 v[146:147], 18, v[144:145]
	s_and_b64 vcc, exec, s[22:23]
	v_lshlrev_b32_e32 v144, 7, v155
	v_lshl_add_u64 v[146:147], s[54:55], 0, v[146:147]
	s_cbranch_vccz .LBB0_925
	v_and_b32_e32 v0, 0x3e000, v144
	v_lshl_add_u64 v[148:149], v[146:147], 0, v[0:1]
	s_and_b64 vcc, exec, s[0:1]
	s_cbranch_vccz .LBB0_922
	v_lshlrev_b32_e32 v0, 3, v245
	v_and_b32_e32 v0, 0x1a0, v0
	v_add_lshl_u32 v156, v152, v0, 3
	v_ashrrev_i32_e32 v157, 31, v156
	v_lshl_add_u64 v[156:157], v[156:157], 1, v[148:149]
	v_and_b32_e32 v0, 8, v245
	v_lshl_add_u64 v[156:157], v[156:157], 0, v[0:1]
	v_lshlrev_b32_e32 v0, 1, v151
	v_lshl_add_u64 v[156:157], v[156:157], 0, v[0:1]
	s_lshl_b32 s31, s66, 2
	s_add_i32 s31, s31, s67
	s_lshl_b32 s31, s31, 10
	s_add_i32 s31, s31, 0x20000
	v_and_b32_e32 v0, 15, v240
	v_lshrrev_b32_e32 v205, 4, v240
	v_bfe_u32 v229, v0, 2, 1
	v_lshl_add_u32 v205, v229, 2, v205
	v_lshlrev_b32_e32 v205, 6, v205
	v_bfe_u32 v229, v0, 3, 1
	v_lshl_add_u32 v205, v229, 2, v205
	v_and_b32_e32 v0, 3, v0
	v_add_lshl_u32 v205, v205, v0, 1
	v_lshlrev_b32_e32 v0, 4, v240
	v_sub_u32_e32 v229, v0, v205
	v_add_u32_e32 v205, s31, v205
	v_add_u32_e32 v0, s31, v0
	ds_write_b16 v205, v130
	ds_write_b16_d16_hi v205, v130 offset:16
	ds_write_b16 v205, v131 offset:32
	ds_write_b16_d16_hi v205, v131 offset:48
	ds_write_b16 v205, v132 offset:64
	ds_write_b16_d16_hi v205, v132 offset:80
	ds_write_b16 v205, v133 offset:96
	ds_write_b16_d16_hi v205, v133 offset:112
	v_ashrrev_i32_e32 v205, 31, v229
	v_add_co_u32_e32 v156, vcc, v156, v229
	s_nop 1
	v_addc_co_u32_e32 v157, vcc, v157, v205, vcc
	s_waitcnt lgkmcnt(0)
	ds_read_b128 v[130:133], v0
	s_waitcnt lgkmcnt(0)
	global_store_dwordx4 v[156:157], v[130:133], off
	s_mov_b64 s[4:5], 0

.LBB0_957:
	s_waitcnt lgkmcnt(0)
	v_add_u32_e32 v63, 16, v141
	v_cndmask_b32_e64 v0, 0, 1, s[14:15]
	v_add_u32_e32 v133, s48, v63
	v_cmp_ne_u32_e64 s[16:17], 1, v0
	v_cndmask_b32_e64 v0, 0, 1, s[42:43]
	v_ashrrev_i32_e32 v144, 11, v133
	v_and_b32_e32 v145, 0x7ff, v133
	v_xor_b32_e32 v132, 16, v153
	s_mov_b64 s[4:5], -1
	s_andn2_b64 vcc, exec, s[14:15]
	v_cmp_ne_u32_e64 s[14:15], 1, v0
	s_cbranch_vccnz .LBB0_972
	v_cvt_pk_bf16_f32 v58, v50, v51
	v_cvt_pk_bf16_f32 v59, v52, v53
	v_cvt_pk_bf16_f32 v60, v54, v55
	v_cvt_pk_bf16_f32 v61, v56, v57
	s_and_b64 vcc, exec, s[14:15]
	s_cbranch_vccnz .LBB0_968
	v_mov_b32_e32 v0, s29
	v_mad_i32_i24 v64, s30, v144, v0
	v_ashrrev_i32_e32 v65, 31, v64
	v_lshlrev_b64 v[64:65], 18, v[64:65]
	s_andn2_b64 vcc, exec, s[22:23]
	v_lshlrev_b32_e32 v62, 7, v145
	v_lshl_add_u64 v[64:65], s[54:55], 0, v[64:65]
	s_cbranch_vccnz .LBB0_965
	v_and_b32_e32 v0, 0x3e000, v62
	v_lshl_add_u64 v[130:131], v[64:65], 0, v[0:1]
	s_andn2_b64 vcc, exec, s[0:1]
	s_cbranch_vccnz .LBB0_962
	v_lshlrev_b32_e32 v146, 3, v245
	v_lshlrev_b32_e32 v0, 3, v63
	v_and_b32_e32 v146, 32, v146
	v_and_b32_e32 v0, 0x180, v0
	v_add_u32_e32 v146, v152, v146
	v_add_lshl_u32 v146, v146, v0, 3
	v_ashrrev_i32_e32 v147, 31, v146
	v_lshl_add_u64 v[146:147], v[146:147], 1, v[130:131]
	v_and_b32_e32 v0, 8, v245
	v_lshl_add_u64 v[146:147], v[146:147], 0, v[0:1]
	v_lshlrev_b32_e32 v0, 1, v151
	v_lshl_add_u64 v[146:147], v[146:147], 0, v[0:1]
	s_mov_b64 s[4:5], 0
	s_lshl_b32 s31, s66, 2
	s_add_i32 s31, s31, s67
	s_lshl_b32 s31, s31, 10
	s_add_i32 s31, s31, 0x20000
	v_and_b32_e32 v0, 15, v240
	v_lshrrev_b32_e32 v205, 4, v240
	v_bfe_u32 v229, v0, 2, 1
	v_lshl_add_u32 v205, v229, 2, v205
	v_lshlrev_b32_e32 v205, 6, v205
	v_bfe_u32 v229, v0, 3, 1
	v_lshl_add_u32 v205, v229, 2, v205
	v_and_b32_e32 v0, 3, v0
	v_add_lshl_u32 v205, v205, v0, 1
	v_lshlrev_b32_e32 v0, 4, v240
	v_sub_u32_e32 v229, v0, v205
	v_add_u32_e32 v205, s31, v205
	v_add_u32_e32 v0, s31, v0
	ds_write_b16 v205, v58
	ds_write_b16_d16_hi v205, v58 offset:16
	ds_write_b16 v205, v59 offset:32
	ds_write_b16_d16_hi v205, v59 offset:48
	ds_write_b16 v205, v60 offset:64
	ds_write_b16_d16_hi v205, v60 offset:80
	ds_write_b16 v205, v61 offset:96
	ds_write_b16_d16_hi v205, v61 offset:112
	v_ashrrev_i32_e32 v205, 31, v229
	v_add_co_u32_e32 v146, vcc, v146, v229
	s_nop 1
	v_addc_co_u32_e32 v147, vcc, v147, v205, vcc
	s_waitcnt lgkmcnt(0)
	ds_read_b128 v[58:61], v0
	s_waitcnt lgkmcnt(0)
	global_store_dwordx4 v[146:147], v[58:61], off

.LBB0_997:
	s_waitcnt lgkmcnt(0)
	v_add_u32_e32 v55, 32, v141
	v_add_u32_e32 v60, s48, v55
	v_ashrrev_i32_e32 v61, 11, v60
	v_and_b32_e32 v62, 0x7ff, v60
	s_and_b64 vcc, exec, s[16:17]
	s_mov_b64 s[4:5], -1
	s_cbranch_vccnz .LBB0_1012
	v_cvt_pk_bf16_f32 v50, v42, v43
	v_cvt_pk_bf16_f32 v51, v44, v45
	v_cvt_pk_bf16_f32 v52, v46, v47
	v_cvt_pk_bf16_f32 v53, v48, v49
	s_and_b64 vcc, exec, s[14:15]
	s_cbranch_vccnz .LBB0_1008
	v_mov_b32_e32 v0, s29
	v_mad_i32_i24 v56, s30, v61, v0
	v_ashrrev_i32_e32 v57, 31, v56
	v_lshlrev_b64 v[56:57], 18, v[56:57]
	s_andn2_b64 vcc, exec, s[22:23]
	v_lshlrev_b32_e32 v54, 7, v62
	v_lshl_add_u64 v[56:57], s[54:55], 0, v[56:57]
	s_cbranch_vccnz .LBB0_1005
	v_and_b32_e32 v0, 0x3e000, v54
	v_lshl_add_u64 v[58:59], v[56:57], 0, v[0:1]
	s_andn2_b64 vcc, exec, s[0:1]
	s_cbranch_vccnz .LBB0_1002
	v_lshlrev_b32_e32 v63, 3, v245
	v_lshlrev_b32_e32 v0, 3, v55
	v_and_b32_e32 v63, 32, v63
	v_and_b32_e32 v0, 0x180, v0
	v_add_u32_e32 v63, v152, v63
	v_add_lshl_u32 v64, v63, v0, 3
	v_ashrrev_i32_e32 v65, 31, v64
	v_lshl_add_u64 v[64:65], v[64:65], 1, v[58:59]
	v_and_b32_e32 v0, 8, v245
	v_lshl_add_u64 v[64:65], v[64:65], 0, v[0:1]
	v_lshlrev_b32_e32 v0, 1, v151
	v_lshl_add_u64 v[64:65], v[64:65], 0, v[0:1]
	s_mov_b64 s[4:5], 0
	s_lshl_b32 s31, s66, 2
	s_add_i32 s31, s31, s67
	s_lshl_b32 s31, s31, 10
	s_add_i32 s31, s31, 0x20000
	v_and_b32_e32 v0, 15, v240
	v_lshrrev_b32_e32 v205, 4, v240
	v_bfe_u32 v229, v0, 2, 1
	v_lshl_add_u32 v205, v229, 2, v205
	v_lshlrev_b32_e32 v205, 6, v205
	v_bfe_u32 v229, v0, 3, 1
	v_lshl_add_u32 v205, v229, 2, v205
	v_and_b32_e32 v0, 3, v0
	v_add_lshl_u32 v205, v205, v0, 1
	v_lshlrev_b32_e32 v0, 4, v240
	v_sub_u32_e32 v229, v0, v205
	v_add_u32_e32 v205, s31, v205
	v_add_u32_e32 v0, s31, v0
	ds_write_b16 v205, v50
	ds_write_b16_d16_hi v205, v50 offset:16
	ds_write_b16 v205, v51 offset:32
	ds_write_b16_d16_hi v205, v51 offset:48
	ds_write_b16 v205, v52 offset:64
	ds_write_b16_d16_hi v205, v52 offset:80
	ds_write_b16 v205, v53 offset:96
	ds_write_b16_d16_hi v205, v53 offset:112
	v_ashrrev_i32_e32 v205, 31, v229
	v_add_co_u32_e32 v64, vcc, v64, v229
	s_nop 1
	v_addc_co_u32_e32 v65, vcc, v65, v205, vcc
	s_waitcnt lgkmcnt(0)
	ds_read_b128 v[50:53], v0
	s_waitcnt lgkmcnt(0)
	global_store_dwordx4 v[64:65], v[50:53], off

.LBB0_1037:
	s_waitcnt lgkmcnt(0)
	v_add_u32_e32 v47, 48, v141
	v_add_u32_e32 v52, s48, v47
	v_ashrrev_i32_e32 v53, 11, v52
	v_and_b32_e32 v54, 0x7ff, v52
	s_and_b64 vcc, exec, s[16:17]
	s_mov_b64 s[4:5], -1
	s_cbranch_vccnz .LBB0_1053
	v_cvt_pk_bf16_f32 v42, v34, v35
	v_cvt_pk_bf16_f32 v43, v36, v37
	v_cvt_pk_bf16_f32 v44, v38, v39
	v_cvt_pk_bf16_f32 v45, v40, v41
	s_and_b64 vcc, exec, s[14:15]
	s_cbranch_vccnz .LBB0_1048
	v_mov_b32_e32 v0, s29
	v_mad_i32_i24 v48, s30, v53, v0
	v_ashrrev_i32_e32 v49, 31, v48
	v_lshlrev_b64 v[48:49], 18, v[48:49]
	s_andn2_b64 vcc, exec, s[22:23]
	v_lshlrev_b32_e32 v46, 7, v54
	v_lshl_add_u64 v[48:49], s[54:55], 0, v[48:49]
	s_cbranch_vccnz .LBB0_1045
	v_and_b32_e32 v0, 0x3e000, v46
	v_lshl_add_u64 v[50:51], v[48:49], 0, v[0:1]
	s_andn2_b64 vcc, exec, s[0:1]
	s_cbranch_vccnz .LBB0_1042
	v_lshlrev_b32_e32 v55, 3, v245
	v_lshlrev_b32_e32 v0, 3, v47
	v_and_b32_e32 v55, 32, v55
	v_and_b32_e32 v0, 0x180, v0
	v_add_u32_e32 v55, v152, v55
	v_add_lshl_u32 v56, v55, v0, 3
	v_ashrrev_i32_e32 v57, 31, v56
	v_lshl_add_u64 v[56:57], v[56:57], 1, v[50:51]
	v_and_b32_e32 v0, 8, v245
	v_lshl_add_u64 v[56:57], v[56:57], 0, v[0:1]
	v_lshlrev_b32_e32 v0, 1, v151
	v_lshl_add_u64 v[56:57], v[56:57], 0, v[0:1]
	s_mov_b64 s[4:5], 0
	s_lshl_b32 s31, s66, 2
	s_add_i32 s31, s31, s67
	s_lshl_b32 s31, s31, 10
	s_add_i32 s31, s31, 0x20000
	v_and_b32_e32 v0, 15, v240
	v_lshrrev_b32_e32 v205, 4, v240
	v_bfe_u32 v229, v0, 2, 1
	v_lshl_add_u32 v205, v229, 2, v205
	v_lshlrev_b32_e32 v205, 6, v205
	v_bfe_u32 v229, v0, 3, 1
	v_lshl_add_u32 v205, v229, 2, v205
	v_and_b32_e32 v0, 3, v0
	v_add_lshl_u32 v205, v205, v0, 1
	v_lshlrev_b32_e32 v0, 4, v240
	v_sub_u32_e32 v229, v0, v205
	v_add_u32_e32 v205, s31, v205
	v_add_u32_e32 v0, s31, v0
	ds_write_b16 v205, v42
	ds_write_b16_d16_hi v205, v42 offset:16
	ds_write_b16 v205, v43 offset:32
	ds_write_b16_d16_hi v205, v43 offset:48
	ds_write_b16 v205, v44 offset:64
	ds_write_b16_d16_hi v205, v44 offset:80
	ds_write_b16 v205, v45 offset:96
	ds_write_b16_d16_hi v205, v45 offset:112
	v_ashrrev_i32_e32 v205, 31, v229
	v_add_co_u32_e32 v56, vcc, v56, v229
	s_nop 1
	v_addc_co_u32_e32 v57, vcc, v57, v205, vcc
	s_waitcnt lgkmcnt(0)
	ds_read_b128 v[42:45], v0
	s_waitcnt lgkmcnt(0)
	global_store_dwordx4 v[56:57], v[42:45], off

.LBB0_1079:
	s_waitcnt lgkmcnt(0)
	v_ashrrev_i32_e32 v39, 11, v38
	v_and_b32_e32 v46, 0x7ff, v38
	s_and_b64 vcc, exec, s[16:17]
	s_mov_b64 s[4:5], -1
	s_cbranch_vccnz .LBB0_1094
	v_cvt_pk_bf16_f32 v34, v26, v27
	v_cvt_pk_bf16_f32 v35, v28, v29
	v_cvt_pk_bf16_f32 v36, v30, v31
	v_cvt_pk_bf16_f32 v37, v32, v33
	s_and_b64 vcc, exec, s[14:15]
	s_cbranch_vccnz .LBB0_1090
	v_mov_b32_e32 v0, s29
	v_mad_i32_i24 v40, s30, v39, v0
	v_ashrrev_i32_e32 v41, 31, v40
	v_lshlrev_b64 v[42:43], 18, v[40:41]
	s_andn2_b64 vcc, exec, s[22:23]
	v_lshlrev_b32_e32 v40, 7, v46
	v_lshl_add_u64 v[42:43], s[54:55], 0, v[42:43]
	s_cbranch_vccnz .LBB0_1087
	v_and_b32_e32 v0, 0x3e000, v40
	v_lshl_add_u64 v[44:45], v[42:43], 0, v[0:1]
	s_andn2_b64 vcc, exec, s[0:1]
	s_cbranch_vccnz .LBB0_1084
	v_lshlrev_b32_e32 v0, 3, v245
	v_and_b32_e32 v0, 0x1a0, v0
	v_add_lshl_u32 v48, v152, v0, 3
	v_ashrrev_i32_e32 v49, 31, v48
	v_lshl_add_u64 v[48:49], v[48:49], 1, v[44:45]
	v_and_b32_e32 v0, 8, v245
	v_lshl_add_u64 v[48:49], v[48:49], 0, v[0:1]
	v_lshlrev_b32_e32 v0, 1, v151
	v_lshl_add_u64 v[48:49], v[48:49], 0, v[0:1]
	s_mov_b64 s[4:5], 0
	s_lshl_b32 s31, s66, 2
	s_add_i32 s31, s31, s67
	s_lshl_b32 s31, s31, 10
	s_add_i32 s31, s31, 0x20000
	v_and_b32_e32 v0, 15, v240
	v_lshrrev_b32_e32 v205, 4, v240
	v_bfe_u32 v229, v0, 2, 1
	v_lshl_add_u32 v205, v229, 2, v205
	v_lshlrev_b32_e32 v205, 6, v205
	v_bfe_u32 v229, v0, 3, 1
	v_lshl_add_u32 v205, v229, 2, v205
	v_and_b32_e32 v0, 3, v0
	v_add_lshl_u32 v205, v205, v0, 1
	v_lshlrev_b32_e32 v0, 4, v240
	v_sub_u32_e32 v229, v0, v205
	v_add_u32_e32 v205, s31, v205
	v_add_u32_e32 v0, s31, v0
	ds_write_b16 v205, v34
	ds_write_b16_d16_hi v205, v34 offset:16
	ds_write_b16 v205, v35 offset:32
	ds_write_b16_d16_hi v205, v35 offset:48
	ds_write_b16 v205, v36 offset:64
	ds_write_b16_d16_hi v205, v36 offset:80
	ds_write_b16 v205, v37 offset:96
	ds_write_b16_d16_hi v205, v37 offset:112
	v_ashrrev_i32_e32 v205, 31, v229
	v_add_co_u32_e32 v48, vcc, v48, v229
	s_nop 1
	v_addc_co_u32_e32 v49, vcc, v49, v205, vcc
	s_waitcnt lgkmcnt(0)
	ds_read_b128 v[34:37], v0
	s_waitcnt lgkmcnt(0)
	global_store_dwordx4 v[48:49], v[34:37], off

.LBB0_1119:
	s_waitcnt lgkmcnt(0)
	v_add_u32_e32 v31, 0x90, v141
	v_add_u32_e32 v36, s48, v31
	v_ashrrev_i32_e32 v37, 11, v36
	v_and_b32_e32 v38, 0x7ff, v36
	s_and_b64 vcc, exec, s[16:17]
	s_mov_b64 s[4:5], -1
	s_cbranch_vccnz .LBB0_1134
	v_cvt_pk_bf16_f32 v26, v18, v19
	v_cvt_pk_bf16_f32 v27, v20, v21
	v_cvt_pk_bf16_f32 v28, v22, v23
	v_cvt_pk_bf16_f32 v29, v24, v25
	s_and_b64 vcc, exec, s[14:15]
	s_cbranch_vccnz .LBB0_1130
	v_mov_b32_e32 v0, s29
	v_mad_i32_i24 v32, s30, v37, v0
	v_ashrrev_i32_e32 v33, 31, v32
	v_lshlrev_b64 v[32:33], 18, v[32:33]
	s_andn2_b64 vcc, exec, s[22:23]
	v_lshlrev_b32_e32 v30, 7, v38
	v_lshl_add_u64 v[32:33], s[54:55], 0, v[32:33]
	s_cbranch_vccnz .LBB0_1127
	v_and_b32_e32 v0, 0x3e000, v30
	v_lshl_add_u64 v[34:35], v[32:33], 0, v[0:1]
	s_andn2_b64 vcc, exec, s[0:1]
	s_cbranch_vccnz .LBB0_1124
	v_lshlrev_b32_e32 v39, 3, v245
	v_lshlrev_b32_e32 v0, 3, v31
	v_and_b32_e32 v39, 32, v39
	v_and_b32_e32 v0, 0x180, v0
	v_add_u32_e32 v39, v152, v39
	v_add_lshl_u32 v40, v39, v0, 3
	v_ashrrev_i32_e32 v41, 31, v40
	v_lshl_add_u64 v[40:41], v[40:41], 1, v[34:35]
	v_and_b32_e32 v0, 8, v245
	v_lshl_add_u64 v[40:41], v[40:41], 0, v[0:1]
	v_lshlrev_b32_e32 v0, 1, v151
	v_lshl_add_u64 v[40:41], v[40:41], 0, v[0:1]
	s_mov_b64 s[4:5], 0
	s_lshl_b32 s31, s66, 2
	s_add_i32 s31, s31, s67
	s_lshl_b32 s31, s31, 10
	s_add_i32 s31, s31, 0x20000
	v_and_b32_e32 v0, 15, v240
	v_lshrrev_b32_e32 v205, 4, v240
	v_bfe_u32 v229, v0, 2, 1
	v_lshl_add_u32 v205, v229, 2, v205
	v_lshlrev_b32_e32 v205, 6, v205
	v_bfe_u32 v229, v0, 3, 1
	v_lshl_add_u32 v205, v229, 2, v205
	v_and_b32_e32 v0, 3, v0
	v_add_lshl_u32 v205, v205, v0, 1
	v_lshlrev_b32_e32 v0, 4, v240
	v_sub_u32_e32 v229, v0, v205
	v_add_u32_e32 v205, s31, v205
	v_add_u32_e32 v0, s31, v0
	ds_write_b16 v205, v26
	ds_write_b16_d16_hi v205, v26 offset:16
	ds_write_b16 v205, v27 offset:32
	ds_write_b16_d16_hi v205, v27 offset:48
	ds_write_b16 v205, v28 offset:64
	ds_write_b16_d16_hi v205, v28 offset:80
	ds_write_b16 v205, v29 offset:96
	ds_write_b16_d16_hi v205, v29 offset:112
	v_ashrrev_i32_e32 v205, 31, v229
	v_add_co_u32_e32 v40, vcc, v40, v229
	s_nop 1
	v_addc_co_u32_e32 v41, vcc, v41, v205, vcc
	s_waitcnt lgkmcnt(0)
	ds_read_b128 v[26:29], v0
	s_waitcnt lgkmcnt(0)
	global_store_dwordx4 v[40:41], v[26:29], off

.LBB0_1159:
	s_waitcnt lgkmcnt(0)
	v_add_u32_e32 v23, 0xa0, v141
	v_add_u32_e32 v28, s48, v23
	v_ashrrev_i32_e32 v29, 11, v28
	v_and_b32_e32 v30, 0x7ff, v28
	s_and_b64 vcc, exec, s[16:17]
	s_mov_b64 s[4:5], -1
	s_cbranch_vccnz .LBB0_1174
	v_cvt_pk_bf16_f32 v18, v10, v11
	v_cvt_pk_bf16_f32 v19, v12, v13
	v_cvt_pk_bf16_f32 v20, v14, v15
	v_cvt_pk_bf16_f32 v21, v16, v17
	s_and_b64 vcc, exec, s[14:15]
	s_cbranch_vccnz .LBB0_1170
	v_mov_b32_e32 v0, s29
	v_mad_i32_i24 v24, s30, v29, v0
	v_ashrrev_i32_e32 v25, 31, v24
	v_lshlrev_b64 v[24:25], 18, v[24:25]
	s_andn2_b64 vcc, exec, s[22:23]
	v_lshlrev_b32_e32 v22, 7, v30
	v_lshl_add_u64 v[24:25], s[54:55], 0, v[24:25]
	s_cbranch_vccnz .LBB0_1167
	v_and_b32_e32 v0, 0x3e000, v22
	v_lshl_add_u64 v[26:27], v[24:25], 0, v[0:1]
	s_andn2_b64 vcc, exec, s[0:1]
	s_cbranch_vccnz .LBB0_1164
	v_lshlrev_b32_e32 v31, 3, v245
	v_lshlrev_b32_e32 v0, 3, v23
	v_and_b32_e32 v31, 32, v31
	v_and_b32_e32 v0, 0x180, v0
	v_add_u32_e32 v31, v152, v31
	v_add_lshl_u32 v32, v31, v0, 3
	v_ashrrev_i32_e32 v33, 31, v32
	v_lshl_add_u64 v[32:33], v[32:33], 1, v[26:27]
	v_and_b32_e32 v0, 8, v245
	v_lshl_add_u64 v[32:33], v[32:33], 0, v[0:1]
	v_lshlrev_b32_e32 v0, 1, v151
	v_lshl_add_u64 v[32:33], v[32:33], 0, v[0:1]
	s_mov_b64 s[4:5], 0
	s_lshl_b32 s31, s66, 2
	s_add_i32 s31, s31, s67
	s_lshl_b32 s31, s31, 10
	s_add_i32 s31, s31, 0x20000
	v_and_b32_e32 v0, 15, v240
	v_lshrrev_b32_e32 v205, 4, v240
	v_bfe_u32 v229, v0, 2, 1
	v_lshl_add_u32 v205, v229, 2, v205
	v_lshlrev_b32_e32 v205, 6, v205
	v_bfe_u32 v229, v0, 3, 1
	v_lshl_add_u32 v205, v229, 2, v205
	v_and_b32_e32 v0, 3, v0
	v_add_lshl_u32 v205, v205, v0, 1
	v_lshlrev_b32_e32 v0, 4, v240
	v_sub_u32_e32 v229, v0, v205
	v_add_u32_e32 v205, s31, v205
	v_add_u32_e32 v0, s31, v0
	ds_write_b16 v205, v18
	ds_write_b16_d16_hi v205, v18 offset:16
	ds_write_b16 v205, v19 offset:32
	ds_write_b16_d16_hi v205, v19 offset:48
	ds_write_b16 v205, v20 offset:64
	ds_write_b16_d16_hi v205, v20 offset:80
	ds_write_b16 v205, v21 offset:96
	ds_write_b16_d16_hi v205, v21 offset:112
	v_ashrrev_i32_e32 v205, 31, v229
	v_add_co_u32_e32 v32, vcc, v32, v229
	s_nop 1
	v_addc_co_u32_e32 v33, vcc, v33, v205, vcc
	s_waitcnt lgkmcnt(0)
	ds_read_b128 v[18:21], v0
	s_waitcnt lgkmcnt(0)
	global_store_dwordx4 v[32:33], v[18:21], off

.LBB0_1199:
	s_waitcnt lgkmcnt(0)
	v_add_u32_e32 v15, 0xb0, v141
	v_add_u32_e32 v20, s48, v15
	v_ashrrev_i32_e32 v21, 11, v20
	v_and_b32_e32 v22, 0x7ff, v20
	s_and_b64 vcc, exec, s[16:17]
	s_mov_b64 s[4:5], -1
	s_cbranch_vccnz .LBB0_1213
	v_cvt_pk_bf16_f32 v10, v2, v3
	v_cvt_pk_bf16_f32 v11, v4, v5
	v_cvt_pk_bf16_f32 v12, v6, v7
	v_cvt_pk_bf16_f32 v13, v8, v9
	s_and_b64 vcc, exec, s[14:15]
	s_cbranch_vccnz .LBB0_1210
	v_mov_b32_e32 v0, s29
	v_mad_i32_i24 v16, s30, v21, v0
	v_ashrrev_i32_e32 v17, 31, v16
	v_lshlrev_b64 v[16:17], 18, v[16:17]
	s_andn2_b64 vcc, exec, s[22:23]
	v_lshlrev_b32_e32 v14, 7, v22
	v_lshl_add_u64 v[16:17], s[54:55], 0, v[16:17]
	s_cbranch_vccnz .LBB0_1207
	v_and_b32_e32 v0, 0x3e000, v14
	v_lshl_add_u64 v[18:19], v[16:17], 0, v[0:1]
	s_andn2_b64 vcc, exec, s[0:1]
	s_mov_b64 s[0:1], -1
	s_cbranch_vccnz .LBB0_1204
	v_lshlrev_b32_e32 v23, 3, v245
	v_lshlrev_b32_e32 v0, 3, v15
	v_and_b32_e32 v23, 32, v23
	v_and_b32_e32 v0, 0x180, v0
	v_add_u32_e32 v23, v152, v23
	v_add_lshl_u32 v24, v23, v0, 3
	v_ashrrev_i32_e32 v25, 31, v24
	v_lshl_add_u64 v[24:25], v[24:25], 1, v[18:19]
	v_and_b32_e32 v0, 8, v245
	v_lshl_add_u64 v[24:25], v[24:25], 0, v[0:1]
	v_lshlrev_b32_e32 v0, 1, v151
	v_lshl_add_u64 v[24:25], v[24:25], 0, v[0:1]
	s_mov_b64 s[0:1], 0
	s_lshl_b32 s31, s66, 2
	s_add_i32 s31, s31, s67
	s_lshl_b32 s31, s31, 10
	s_add_i32 s31, s31, 0x20000
	v_and_b32_e32 v0, 15, v240
	v_lshrrev_b32_e32 v205, 4, v240
	v_bfe_u32 v229, v0, 2, 1
	v_lshl_add_u32 v205, v229, 2, v205
	v_lshlrev_b32_e32 v205, 6, v205
	v_bfe_u32 v229, v0, 3, 1
	v_lshl_add_u32 v205, v229, 2, v205
	v_and_b32_e32 v0, 3, v0
	v_add_lshl_u32 v205, v205, v0, 1
	v_lshlrev_b32_e32 v0, 4, v240
	v_sub_u32_e32 v229, v0, v205
	v_add_u32_e32 v205, s31, v205
	v_add_u32_e32 v0, s31, v0
	ds_write_b16 v205, v10
	ds_write_b16_d16_hi v205, v10 offset:16
	ds_write_b16 v205, v11 offset:32
	ds_write_b16_d16_hi v205, v11 offset:48
	ds_write_b16 v205, v12 offset:64
	ds_write_b16_d16_hi v205, v12 offset:80
	ds_write_b16 v205, v13 offset:96
	ds_write_b16_d16_hi v205, v13 offset:112
	v_ashrrev_i32_e32 v205, 31, v229
	v_add_co_u32_e32 v24, vcc, v24, v229
	s_nop 1
	v_addc_co_u32_e32 v25, vcc, v25, v205, vcc
	s_waitcnt lgkmcnt(0)
	ds_read_b128 v[10:13], v0
	s_waitcnt lgkmcnt(0)
	global_store_dwordx4 v[24:25], v[10:13], off
